# previous version plus: all s_setprio removed from the four GEMM K-loops
# speedup vs baseline: 1.0317x; 1.0062x over previous
.LBB0_131:
	ds_read_b128 v[146:149], v157
	ds_read_b128 v[150:153], v157 offset:1024
	ds_read_b128 v[160:163], v157 offset:2048
	ds_read_b128 v[164:167], v157 offset:3072
	ds_read_b128 v[168:171], v158
	ds_read_b128 v[172:175], v158 offset:1024
	ds_read_b128 v[176:179], v158 offset:2048
	ds_read_b128 v[180:183], v158 offset:3072
	s_add_u32 s34, s30, 0xfff80080
	s_addc_u32 s35, s31, -1
	s_cmp_eq_u32 s55, 28
	s_cselect_b32 s37, s23, s35
	s_cselect_b32 s36, s51, s34
	s_cselect_b32 s35, s21, s54
	s_cselect_b32 s34, s52, s53
	v_lshl_add_u64 v[216:217], s[30:31], 0, v[138:139]
	s_add_i32 m0, s29, 0xc000
	ds_read_b128 v[184:187], v159
	ds_read_b128 v[188:191], v159 offset:1024
	ds_read_b128 v[192:195], v159 offset:2048
	ds_read_b128 v[196:199], v159 offset:3072
	ds_read_b128 v[200:203], v159 offset:4096
	ds_read_b128 v[204:207], v159 offset:5120
	ds_read_b128 v[208:211], v159 offset:6144
	ds_read_b128 v[212:215], v159 offset:7168
	global_load_lds_dwordx4 v[216:217], off
	v_lshl_add_u64 v[216:217], s[30:31], 0, v[140:141]
	s_add_i32 m0, s29, 0xe000
	s_nop 0
	global_load_lds_dwordx4 v[216:217], off
	s_waitcnt vmcnt(8)
	s_waitcnt lgkmcnt(0)
	s_barrier
	s_waitcnt lgkmcnt(0)
	v_mfma_f32_16x16x32_bf16 v[124:127], v[146:149], v[184:187], v[124:127]
	v_mfma_f32_16x16x32_bf16 v[124:127], v[150:153], v[188:191], v[124:127]
	v_mfma_f32_16x16x32_bf16 v[120:123], v[160:163], v[184:187], v[120:123]
	v_mfma_f32_16x16x32_bf16 v[120:123], v[164:167], v[188:191], v[120:123]
	v_mfma_f32_16x16x32_bf16 v[104:107], v[160:163], v[192:195], v[104:107]
	v_mfma_f32_16x16x32_bf16 v[104:107], v[164:167], v[196:199], v[104:107]
	v_mfma_f32_16x16x32_bf16 v[108:111], v[146:149], v[192:195], v[108:111]
	v_mfma_f32_16x16x32_bf16 v[108:111], v[150:153], v[196:199], v[108:111]
	v_mfma_f32_16x16x32_bf16 v[92:95], v[146:149], v[200:203], v[92:95]
	v_mfma_f32_16x16x32_bf16 v[92:95], v[150:153], v[204:207], v[92:95]
	v_mfma_f32_16x16x32_bf16 v[88:91], v[160:163], v[200:203], v[88:91]
	v_mfma_f32_16x16x32_bf16 v[88:91], v[164:167], v[204:207], v[88:91]
	v_mfma_f32_16x16x32_bf16 v[72:75], v[160:163], v[208:211], v[72:75]
	v_mfma_f32_16x16x32_bf16 v[72:75], v[164:167], v[212:215], v[72:75]
	v_mfma_f32_16x16x32_bf16 v[76:79], v[146:149], v[208:211], v[76:79]
	v_mfma_f32_16x16x32_bf16 v[76:79], v[150:153], v[212:215], v[76:79]
	v_mfma_f32_16x16x32_bf16 v[116:119], v[168:171], v[184:187], v[116:119]
	v_mfma_f32_16x16x32_bf16 v[116:119], v[172:175], v[188:191], v[116:119]
	v_mfma_f32_16x16x32_bf16 v[112:115], v[176:179], v[184:187], v[112:115]
	v_mfma_f32_16x16x32_bf16 v[112:115], v[180:183], v[188:191], v[112:115]
	v_mfma_f32_16x16x32_bf16 v[96:99], v[176:179], v[192:195], v[96:99]
	v_mfma_f32_16x16x32_bf16 v[96:99], v[180:183], v[196:199], v[96:99]
	v_mfma_f32_16x16x32_bf16 v[100:103], v[168:171], v[192:195], v[100:103]
	v_mfma_f32_16x16x32_bf16 v[100:103], v[172:175], v[196:199], v[100:103]
	v_mfma_f32_16x16x32_bf16 v[84:87], v[168:171], v[200:203], v[84:87]
	v_mfma_f32_16x16x32_bf16 v[84:87], v[172:175], v[204:207], v[84:87]
	v_mfma_f32_16x16x32_bf16 v[80:83], v[176:179], v[200:203], v[80:83]
	v_mfma_f32_16x16x32_bf16 v[80:83], v[180:183], v[204:207], v[80:83]
	v_mfma_f32_16x16x32_bf16 v[64:67], v[176:179], v[208:211], v[64:67]
	v_mfma_f32_16x16x32_bf16 v[64:67], v[180:183], v[212:215], v[64:67]
	v_mfma_f32_16x16x32_bf16 v[68:71], v[168:171], v[208:211], v[68:71]
	v_mfma_f32_16x16x32_bf16 v[68:71], v[172:175], v[212:215], v[68:71]
	s_barrier
	s_add_i32 s56, s47, s33
	v_lshl_add_u64 v[216:217], s[34:35], 0, v[134:135]
	s_mov_b32 m0, s56
	ds_read_b128 v[184:187], v159 offset:16384
	ds_read_b128 v[188:191], v159 offset:17408
	ds_read_b128 v[192:195], v159 offset:18432
	ds_read_b128 v[196:199], v159 offset:19456
	ds_read_b128 v[200:203], v159 offset:20480
	ds_read_b128 v[204:207], v159 offset:21504
	ds_read_b128 v[208:211], v159 offset:22528
	ds_read_b128 v[212:215], v159 offset:23552
	global_load_lds_dwordx4 v[216:217], off
	s_add_i32 m0, s56, 0x2000
	s_add_u32 s56, s34, 0x80000
	v_lshl_add_u64 v[218:219], s[34:35], 0, v[130:131]
	s_addc_u32 s57, s35, 0
	s_add_i32 s58, s48, s33
	global_load_lds_dwordx4 v[218:219], off
	v_lshl_add_u64 v[220:221], s[56:57], 0, v[134:135]
	s_mov_b32 m0, s58
	v_lshl_add_u64 v[222:223], s[36:37], 0, v[132:133]
	global_load_lds_dwordx4 v[220:221], off
	v_lshl_add_u64 v[220:221], s[56:57], 0, v[130:131]
	s_add_i32 m0, s58, 0x2000
	s_nop 0
	global_load_lds_dwordx4 v[220:221], off
	v_lshl_add_u64 v[220:221], s[36:37], 0, v[136:137]
	s_mov_b32 m0, s29
	s_nop 0
	global_load_lds_dwordx4 v[220:221], off
	s_mov_b32 m0, s40
	s_nop 0
	global_load_lds_dwordx4 v[222:223], off
	s_waitcnt vmcnt(8)
	s_waitcnt lgkmcnt(0)
	s_barrier
	s_waitcnt lgkmcnt(0)
	v_mfma_f32_16x16x32_bf16 v[60:63], v[146:149], v[184:187], v[60:63]
	v_mfma_f32_16x16x32_bf16 v[60:63], v[150:153], v[188:191], v[60:63]
	v_mfma_f32_16x16x32_bf16 v[56:59], v[160:163], v[184:187], v[56:59]
	v_mfma_f32_16x16x32_bf16 v[56:59], v[164:167], v[188:191], v[56:59]
	v_mfma_f32_16x16x32_bf16 v[40:43], v[160:163], v[192:195], v[40:43]
	v_mfma_f32_16x16x32_bf16 v[40:43], v[164:167], v[196:199], v[40:43]
	v_mfma_f32_16x16x32_bf16 v[44:47], v[146:149], v[192:195], v[44:47]
	v_mfma_f32_16x16x32_bf16 v[44:47], v[150:153], v[196:199], v[44:47]
	v_mfma_f32_16x16x32_bf16 v[28:31], v[146:149], v[200:203], v[28:31]
	v_mfma_f32_16x16x32_bf16 v[28:31], v[150:153], v[204:207], v[28:31]
	v_mfma_f32_16x16x32_bf16 v[24:27], v[160:163], v[200:203], v[24:27]
	v_mfma_f32_16x16x32_bf16 v[24:27], v[164:167], v[204:207], v[24:27]
	v_mfma_f32_16x16x32_bf16 v[8:11], v[160:163], v[208:211], v[8:11]
	v_mfma_f32_16x16x32_bf16 v[8:11], v[164:167], v[212:215], v[8:11]
	v_mfma_f32_16x16x32_bf16 v[12:15], v[146:149], v[208:211], v[12:15]
	v_mfma_f32_16x16x32_bf16 v[12:15], v[150:153], v[212:215], v[12:15]
	v_mfma_f32_16x16x32_bf16 v[52:55], v[168:171], v[184:187], v[52:55]
	v_mfma_f32_16x16x32_bf16 v[52:55], v[172:175], v[188:191], v[52:55]
	v_mfma_f32_16x16x32_bf16 v[48:51], v[176:179], v[184:187], v[48:51]
	v_mfma_f32_16x16x32_bf16 v[48:51], v[180:183], v[188:191], v[48:51]
	v_mfma_f32_16x16x32_bf16 v[32:35], v[176:179], v[192:195], v[32:35]
	v_mfma_f32_16x16x32_bf16 v[32:35], v[180:183], v[196:199], v[32:35]
	v_mfma_f32_16x16x32_bf16 v[36:39], v[168:171], v[192:195], v[36:39]
	v_mfma_f32_16x16x32_bf16 v[36:39], v[172:175], v[196:199], v[36:39]
	v_mfma_f32_16x16x32_bf16 v[20:23], v[168:171], v[200:203], v[20:23]
	v_mfma_f32_16x16x32_bf16 v[20:23], v[172:175], v[204:207], v[20:23]
	v_mfma_f32_16x16x32_bf16 v[16:19], v[176:179], v[200:203], v[16:19]
	v_mfma_f32_16x16x32_bf16 v[16:19], v[180:183], v[204:207], v[16:19]
	v_mfma_f32_16x16x32_bf16 v[0:3], v[176:179], v[208:211], v[0:3]
	v_mfma_f32_16x16x32_bf16 v[0:3], v[180:183], v[212:215], v[0:3]
	v_mfma_f32_16x16x32_bf16 v[4:7], v[168:171], v[208:211], v[4:7]
	v_mfma_f32_16x16x32_bf16 v[4:7], v[172:175], v[212:215], v[4:7]
	s_barrier
	s_add_i32 s56, 0, 0x18000
	s_add_i32 s57, 0, 0x1c000
	v_add_u32_e32 v164, s56, v155
	v_add_u32_e32 v180, s57, v155
	ds_read_b128 v[146:149], v164
	ds_read_b128 v[150:153], v164 offset:1024
	ds_read_b128 v[160:163], v164 offset:2048
	ds_read_b128 v[164:167], v164 offset:3072
	ds_read_b128 v[168:171], v180
	ds_read_b128 v[172:175], v180 offset:1024
	ds_read_b128 v[176:179], v180 offset:2048
	ds_read_b128 v[180:183], v180 offset:3072
	s_add_u32 s36, s36, 0x80000
	s_addc_u32 s37, s37, 0
	s_mov_b32 m0, s41
	v_lshl_add_u64 v[224:225], s[36:37], 0, v[136:137]
	ds_read_b128 v[184:187], v159 offset:32768
	ds_read_b128 v[188:191], v159 offset:33792
	ds_read_b128 v[192:195], v159 offset:34816
	ds_read_b128 v[196:199], v159 offset:35840
	ds_read_b128 v[200:203], v159 offset:36864
	ds_read_b128 v[204:207], v159 offset:37888
	ds_read_b128 v[208:211], v159 offset:38912
	ds_read_b128 v[212:215], v159 offset:39936
	global_load_lds_dwordx4 v[224:225], off
	v_lshl_add_u64 v[224:225], s[36:37], 0, v[132:133]
	s_mov_b32 m0, s42
	s_nop 0
	global_load_lds_dwordx4 v[224:225], off
	s_waitcnt vmcnt(8)
	s_waitcnt lgkmcnt(0)
	s_barrier
	s_waitcnt lgkmcnt(0)
	v_mfma_f32_16x16x32_bf16 v[124:127], v[146:149], v[184:187], v[124:127]
	v_mfma_f32_16x16x32_bf16 v[124:127], v[150:153], v[188:191], v[124:127]
	v_mfma_f32_16x16x32_bf16 v[120:123], v[160:163], v[184:187], v[120:123]
	v_mfma_f32_16x16x32_bf16 v[120:123], v[164:167], v[188:191], v[120:123]
	v_mfma_f32_16x16x32_bf16 v[104:107], v[160:163], v[192:195], v[104:107]
	v_mfma_f32_16x16x32_bf16 v[104:107], v[164:167], v[196:199], v[104:107]
	v_mfma_f32_16x16x32_bf16 v[108:111], v[146:149], v[192:195], v[108:111]
	v_mfma_f32_16x16x32_bf16 v[108:111], v[150:153], v[196:199], v[108:111]
	v_mfma_f32_16x16x32_bf16 v[92:95], v[146:149], v[200:203], v[92:95]
	v_mfma_f32_16x16x32_bf16 v[92:95], v[150:153], v[204:207], v[92:95]
	v_mfma_f32_16x16x32_bf16 v[88:91], v[160:163], v[200:203], v[88:91]
	v_mfma_f32_16x16x32_bf16 v[88:91], v[164:167], v[204:207], v[88:91]
	v_mfma_f32_16x16x32_bf16 v[72:75], v[160:163], v[208:211], v[72:75]
	v_mfma_f32_16x16x32_bf16 v[72:75], v[164:167], v[212:215], v[72:75]
	v_mfma_f32_16x16x32_bf16 v[76:79], v[146:149], v[208:211], v[76:79]
	v_mfma_f32_16x16x32_bf16 v[76:79], v[150:153], v[212:215], v[76:79]
	v_mfma_f32_16x16x32_bf16 v[116:119], v[168:171], v[184:187], v[116:119]
	v_mfma_f32_16x16x32_bf16 v[116:119], v[172:175], v[188:191], v[116:119]
	v_mfma_f32_16x16x32_bf16 v[112:115], v[176:179], v[184:187], v[112:115]
	v_mfma_f32_16x16x32_bf16 v[112:115], v[180:183], v[188:191], v[112:115]
	v_mfma_f32_16x16x32_bf16 v[96:99], v[176:179], v[192:195], v[96:99]
	v_mfma_f32_16x16x32_bf16 v[96:99], v[180:183], v[196:199], v[96:99]
	v_mfma_f32_16x16x32_bf16 v[100:103], v[168:171], v[192:195], v[100:103]
	v_mfma_f32_16x16x32_bf16 v[100:103], v[172:175], v[196:199], v[100:103]
	v_mfma_f32_16x16x32_bf16 v[84:87], v[168:171], v[200:203], v[84:87]
	v_mfma_f32_16x16x32_bf16 v[84:87], v[172:175], v[204:207], v[84:87]
	v_mfma_f32_16x16x32_bf16 v[80:83], v[176:179], v[200:203], v[80:83]
	v_mfma_f32_16x16x32_bf16 v[80:83], v[180:183], v[204:207], v[80:83]
	v_mfma_f32_16x16x32_bf16 v[64:67], v[176:179], v[208:211], v[64:67]
	v_mfma_f32_16x16x32_bf16 v[64:67], v[180:183], v[212:215], v[64:67]
	v_mfma_f32_16x16x32_bf16 v[68:71], v[168:171], v[208:211], v[68:71]
	v_mfma_f32_16x16x32_bf16 v[68:71], v[172:175], v[212:215], v[68:71]
	s_barrier
	s_add_i32 s36, s56, s33
	v_lshl_add_u64 v[216:217], v[216:217], 0, s[14:15]
	s_mov_b32 m0, s36
	ds_read_b128 v[184:187], v159 offset:49152
	ds_read_b128 v[188:191], v159 offset:50176
	ds_read_b128 v[192:195], v159 offset:51200
	ds_read_b128 v[196:199], v159 offset:52224
	ds_read_b128 v[200:203], v159 offset:53248
	ds_read_b128 v[204:207], v159 offset:54272
	ds_read_b128 v[208:211], v159 offset:55296
	ds_read_b128 v[212:215], v159 offset:56320
	global_load_lds_dwordx4 v[216:217], off
	s_add_i32 m0, s36, 0x2000
	s_add_u32 s34, s34, 0x80080
	v_lshl_add_u64 v[216:217], v[218:219], 0, s[14:15]
	s_addc_u32 s35, s35, 0
	s_add_i32 s36, s57, s33
	global_load_lds_dwordx4 v[216:217], off
	v_lshl_add_u64 v[216:217], s[34:35], 0, v[134:135]
	s_mov_b32 m0, s36
	s_nop 0
	global_load_lds_dwordx4 v[216:217], off
	v_lshl_add_u64 v[216:217], s[34:35], 0, v[130:131]
	s_add_i32 m0, s36, 0x2000
	s_nop 0
	global_load_lds_dwordx4 v[216:217], off
	v_lshl_add_u64 v[216:217], v[220:221], 0, s[14:15]
	s_mov_b32 m0, s44
	s_nop 0
	global_load_lds_dwordx4 v[216:217], off
	v_lshl_add_u64 v[216:217], v[222:223], 0, s[14:15]
	s_mov_b32 m0, s45
	s_nop 0
	global_load_lds_dwordx4 v[216:217], off
	s_waitcnt vmcnt(8)
	s_waitcnt lgkmcnt(0)
	s_barrier
	s_waitcnt lgkmcnt(0)
	v_mfma_f32_16x16x32_bf16 v[60:63], v[146:149], v[184:187], v[60:63]
	v_mfma_f32_16x16x32_bf16 v[60:63], v[150:153], v[188:191], v[60:63]
	v_mfma_f32_16x16x32_bf16 v[56:59], v[160:163], v[184:187], v[56:59]
	v_mfma_f32_16x16x32_bf16 v[56:59], v[164:167], v[188:191], v[56:59]
	v_mfma_f32_16x16x32_bf16 v[40:43], v[160:163], v[192:195], v[40:43]
	v_mfma_f32_16x16x32_bf16 v[40:43], v[164:167], v[196:199], v[40:43]
	v_mfma_f32_16x16x32_bf16 v[44:47], v[146:149], v[192:195], v[44:47]
	v_mfma_f32_16x16x32_bf16 v[44:47], v[150:153], v[196:199], v[44:47]
	v_mfma_f32_16x16x32_bf16 v[28:31], v[146:149], v[200:203], v[28:31]
	v_mfma_f32_16x16x32_bf16 v[28:31], v[150:153], v[204:207], v[28:31]
	v_mfma_f32_16x16x32_bf16 v[24:27], v[160:163], v[200:203], v[24:27]
	v_mfma_f32_16x16x32_bf16 v[24:27], v[164:167], v[204:207], v[24:27]
	v_mfma_f32_16x16x32_bf16 v[8:11], v[160:163], v[208:211], v[8:11]
	v_mfma_f32_16x16x32_bf16 v[8:11], v[164:167], v[212:215], v[8:11]
	v_mfma_f32_16x16x32_bf16 v[12:15], v[146:149], v[208:211], v[12:15]
	v_mfma_f32_16x16x32_bf16 v[12:15], v[150:153], v[212:215], v[12:15]
	v_mfma_f32_16x16x32_bf16 v[52:55], v[168:171], v[184:187], v[52:55]
	v_mfma_f32_16x16x32_bf16 v[52:55], v[172:175], v[188:191], v[52:55]
	v_mfma_f32_16x16x32_bf16 v[48:51], v[176:179], v[184:187], v[48:51]
	v_mfma_f32_16x16x32_bf16 v[48:51], v[180:183], v[188:191], v[48:51]
	v_mfma_f32_16x16x32_bf16 v[32:35], v[176:179], v[192:195], v[32:35]
	v_mfma_f32_16x16x32_bf16 v[32:35], v[180:183], v[196:199], v[32:35]
	v_mfma_f32_16x16x32_bf16 v[36:39], v[168:171], v[192:195], v[36:39]
	v_mfma_f32_16x16x32_bf16 v[36:39], v[172:175], v[196:199], v[36:39]
	v_mfma_f32_16x16x32_bf16 v[20:23], v[168:171], v[200:203], v[20:23]
	v_mfma_f32_16x16x32_bf16 v[20:23], v[172:175], v[204:207], v[20:23]
	v_mfma_f32_16x16x32_bf16 v[16:19], v[176:179], v[200:203], v[16:19]
	v_mfma_f32_16x16x32_bf16 v[16:19], v[180:183], v[204:207], v[16:19]
	v_mfma_f32_16x16x32_bf16 v[0:3], v[176:179], v[208:211], v[0:3]
	v_mfma_f32_16x16x32_bf16 v[0:3], v[180:183], v[212:215], v[0:3]
	v_mfma_f32_16x16x32_bf16 v[4:7], v[168:171], v[208:211], v[4:7]
	v_mfma_f32_16x16x32_bf16 v[4:7], v[172:175], v[212:215], v[4:7]
	s_barrier
	s_add_i32 s55, s55, 2
	s_add_u32 s30, s30, 0x100
	s_addc_u32 s31, s31, 0
	s_add_u32 s53, s53, 0x100
	s_addc_u32 s54, s54, 0
	s_cmp_gt_u32 s55, 29
	s_cbranch_scc0 .LBB0_131
	s_and_b64 vcc, exec, s[18:19]
	s_cbranch_vccz .LBB0_134
	s_barrier

.LBB0_585:
	v_add_u32_e32 v166, s42, v152
	v_add_u32_e32 v182, s43, v152
	s_add_u32 s26, s12, s24
	ds_read_b128 v[154:157], v166
	ds_read_b128 v[158:161], v166 offset:1024
	ds_read_b128 v[162:165], v166 offset:2048
	ds_read_b128 v[166:169], v166 offset:3072
	ds_read_b128 v[170:173], v182
	ds_read_b128 v[174:177], v182 offset:1024
	ds_read_b128 v[178:181], v182 offset:2048
	ds_read_b128 v[182:185], v182 offset:3072
	s_addc_u32 s27, s13, s25
	s_add_u32 s26, s26, 0x100
	s_addc_u32 s27, s27, 0
	s_add_u32 s50, s45, s24
	s_addc_u32 s51, s46, s25
	s_cmpk_eq_i32 s24, 0xf00
	s_cselect_b32 s29, s19, s27
	s_cselect_b32 s28, s47, s26
	s_cselect_b32 s27, s17, s51
	s_cselect_b32 s26, s48, s50
	v_lshl_add_u64 v[218:219], v[146:147], 0, s[24:25]
	s_add_i32 m0, s11, 0xc000
	ds_read_b128 v[186:189], v153
	ds_read_b128 v[190:193], v153 offset:1024
	ds_read_b128 v[194:197], v153 offset:2048
	ds_read_b128 v[198:201], v153 offset:3072
	ds_read_b128 v[202:205], v153 offset:4096
	ds_read_b128 v[206:209], v153 offset:5120
	ds_read_b128 v[210:213], v153 offset:6144
	ds_read_b128 v[214:217], v153 offset:7168
	global_load_lds_dwordx4 v[218:219], off
	v_lshl_add_u64 v[218:219], v[148:149], 0, s[24:25]
	s_add_i32 m0, s11, 0xe000
	s_nop 0
	global_load_lds_dwordx4 v[218:219], off
	s_waitcnt vmcnt(8)
	s_waitcnt lgkmcnt(0)
	s_barrier
	s_waitcnt lgkmcnt(0)
	v_mfma_f32_16x16x32_bf16 v[124:127], v[154:157], v[186:189], v[124:127]
	v_mfma_f32_16x16x32_bf16 v[124:127], v[158:161], v[190:193], v[124:127]
	v_mfma_f32_16x16x32_bf16 v[120:123], v[162:165], v[186:189], v[120:123]
	v_mfma_f32_16x16x32_bf16 v[120:123], v[166:169], v[190:193], v[120:123]
	v_mfma_f32_16x16x32_bf16 v[104:107], v[162:165], v[194:197], v[104:107]
	v_mfma_f32_16x16x32_bf16 v[104:107], v[166:169], v[198:201], v[104:107]
	v_mfma_f32_16x16x32_bf16 v[108:111], v[154:157], v[194:197], v[108:111]
	v_mfma_f32_16x16x32_bf16 v[108:111], v[158:161], v[198:201], v[108:111]
	v_mfma_f32_16x16x32_bf16 v[92:95], v[154:157], v[202:205], v[92:95]
	v_mfma_f32_16x16x32_bf16 v[92:95], v[158:161], v[206:209], v[92:95]
	v_mfma_f32_16x16x32_bf16 v[88:91], v[162:165], v[202:205], v[88:91]
	v_mfma_f32_16x16x32_bf16 v[88:91], v[166:169], v[206:209], v[88:91]
	v_mfma_f32_16x16x32_bf16 v[72:75], v[162:165], v[210:213], v[72:75]
	v_mfma_f32_16x16x32_bf16 v[72:75], v[166:169], v[214:217], v[72:75]
	v_mfma_f32_16x16x32_bf16 v[76:79], v[154:157], v[210:213], v[76:79]
	v_mfma_f32_16x16x32_bf16 v[76:79], v[158:161], v[214:217], v[76:79]
	v_mfma_f32_16x16x32_bf16 v[116:119], v[170:173], v[186:189], v[116:119]
	v_mfma_f32_16x16x32_bf16 v[116:119], v[174:177], v[190:193], v[116:119]
	v_mfma_f32_16x16x32_bf16 v[112:115], v[178:181], v[186:189], v[112:115]
	v_mfma_f32_16x16x32_bf16 v[112:115], v[182:185], v[190:193], v[112:115]
	v_mfma_f32_16x16x32_bf16 v[96:99], v[178:181], v[194:197], v[96:99]
	v_mfma_f32_16x16x32_bf16 v[96:99], v[182:185], v[198:201], v[96:99]
	v_mfma_f32_16x16x32_bf16 v[100:103], v[170:173], v[194:197], v[100:103]
	v_mfma_f32_16x16x32_bf16 v[100:103], v[174:177], v[198:201], v[100:103]
	v_mfma_f32_16x16x32_bf16 v[84:87], v[170:173], v[202:205], v[84:87]
	v_mfma_f32_16x16x32_bf16 v[84:87], v[174:177], v[206:209], v[84:87]
	v_mfma_f32_16x16x32_bf16 v[80:83], v[178:181], v[202:205], v[80:83]
	v_mfma_f32_16x16x32_bf16 v[80:83], v[182:185], v[206:209], v[80:83]
	v_mfma_f32_16x16x32_bf16 v[64:67], v[178:181], v[210:213], v[64:67]
	v_mfma_f32_16x16x32_bf16 v[64:67], v[182:185], v[214:217], v[64:67]
	v_mfma_f32_16x16x32_bf16 v[68:71], v[170:173], v[210:213], v[68:71]
	v_mfma_f32_16x16x32_bf16 v[68:71], v[174:177], v[214:217], v[68:71]
	s_barrier
	s_add_i32 s50, s42, s35
	v_lshl_add_u64 v[218:219], s[26:27], 0, v[132:133]
	s_mov_b32 m0, s50
	ds_read_b128 v[186:189], v153 offset:16384
	ds_read_b128 v[190:193], v153 offset:17408
	ds_read_b128 v[194:197], v153 offset:18432
	ds_read_b128 v[198:201], v153 offset:19456
	ds_read_b128 v[202:205], v153 offset:20480
	ds_read_b128 v[206:209], v153 offset:21504
	ds_read_b128 v[210:213], v153 offset:22528
	ds_read_b128 v[214:217], v153 offset:23552
	global_load_lds_dwordx4 v[218:219], off
	s_add_i32 m0, s50, 0x2000
	s_add_u32 s50, s26, 0x80000
	v_lshl_add_u64 v[220:221], s[26:27], 0, v[136:137]
	s_addc_u32 s51, s27, 0
	s_add_i32 s52, s43, s35
	global_load_lds_dwordx4 v[220:221], off
	v_lshl_add_u64 v[222:223], s[50:51], 0, v[132:133]
	s_mov_b32 m0, s52
	v_lshl_add_u64 v[224:225], s[28:29], 0, v[134:135]
	global_load_lds_dwordx4 v[222:223], off
	v_lshl_add_u64 v[222:223], s[50:51], 0, v[136:137]
	s_add_i32 m0, s52, 0x2000
	s_nop 0
	global_load_lds_dwordx4 v[222:223], off
	v_lshl_add_u64 v[222:223], s[28:29], 0, v[130:131]
	s_mov_b32 m0, s11
	s_nop 0
	global_load_lds_dwordx4 v[222:223], off
	s_mov_b32 m0, s36
	s_nop 0
	global_load_lds_dwordx4 v[224:225], off
	s_waitcnt vmcnt(8)
	s_waitcnt lgkmcnt(0)
	s_barrier
	s_waitcnt lgkmcnt(0)
	v_mfma_f32_16x16x32_bf16 v[60:63], v[154:157], v[186:189], v[60:63]
	v_mfma_f32_16x16x32_bf16 v[60:63], v[158:161], v[190:193], v[60:63]
	v_mfma_f32_16x16x32_bf16 v[56:59], v[162:165], v[186:189], v[56:59]
	v_mfma_f32_16x16x32_bf16 v[56:59], v[166:169], v[190:193], v[56:59]
	v_mfma_f32_16x16x32_bf16 v[40:43], v[162:165], v[194:197], v[40:43]
	v_mfma_f32_16x16x32_bf16 v[40:43], v[166:169], v[198:201], v[40:43]
	v_mfma_f32_16x16x32_bf16 v[44:47], v[154:157], v[194:197], v[44:47]
	v_mfma_f32_16x16x32_bf16 v[44:47], v[158:161], v[198:201], v[44:47]
	v_mfma_f32_16x16x32_bf16 v[28:31], v[154:157], v[202:205], v[28:31]
	v_mfma_f32_16x16x32_bf16 v[28:31], v[158:161], v[206:209], v[28:31]
	v_mfma_f32_16x16x32_bf16 v[24:27], v[162:165], v[202:205], v[24:27]
	v_mfma_f32_16x16x32_bf16 v[24:27], v[166:169], v[206:209], v[24:27]
	v_mfma_f32_16x16x32_bf16 v[8:11], v[162:165], v[210:213], v[8:11]
	v_mfma_f32_16x16x32_bf16 v[8:11], v[166:169], v[214:217], v[8:11]
	v_mfma_f32_16x16x32_bf16 v[12:15], v[154:157], v[210:213], v[12:15]
	v_mfma_f32_16x16x32_bf16 v[12:15], v[158:161], v[214:217], v[12:15]
	v_mfma_f32_16x16x32_bf16 v[52:55], v[170:173], v[186:189], v[52:55]
	v_mfma_f32_16x16x32_bf16 v[52:55], v[174:177], v[190:193], v[52:55]
	v_mfma_f32_16x16x32_bf16 v[48:51], v[178:181], v[186:189], v[48:51]
	v_mfma_f32_16x16x32_bf16 v[48:51], v[182:185], v[190:193], v[48:51]
	v_mfma_f32_16x16x32_bf16 v[32:35], v[178:181], v[194:197], v[32:35]
	v_mfma_f32_16x16x32_bf16 v[32:35], v[182:185], v[198:201], v[32:35]
	v_mfma_f32_16x16x32_bf16 v[36:39], v[170:173], v[194:197], v[36:39]
	v_mfma_f32_16x16x32_bf16 v[36:39], v[174:177], v[198:201], v[36:39]
	v_mfma_f32_16x16x32_bf16 v[20:23], v[170:173], v[202:205], v[20:23]
	v_mfma_f32_16x16x32_bf16 v[20:23], v[174:177], v[206:209], v[20:23]
	v_mfma_f32_16x16x32_bf16 v[16:19], v[178:181], v[202:205], v[16:19]
	v_mfma_f32_16x16x32_bf16 v[16:19], v[182:185], v[206:209], v[16:19]
	v_mfma_f32_16x16x32_bf16 v[0:3], v[178:181], v[210:213], v[0:3]
	v_mfma_f32_16x16x32_bf16 v[0:3], v[182:185], v[214:217], v[0:3]
	v_mfma_f32_16x16x32_bf16 v[4:7], v[170:173], v[210:213], v[4:7]
	v_mfma_f32_16x16x32_bf16 v[4:7], v[174:177], v[214:217], v[4:7]
	s_barrier
	s_add_i32 s50, 0, 0x18000
	s_add_i32 s51, 0, 0x1c000
	v_add_u32_e32 v166, s50, v152
	v_add_u32_e32 v182, s51, v152
	ds_read_b128 v[154:157], v166
	ds_read_b128 v[158:161], v166 offset:1024
	ds_read_b128 v[162:165], v166 offset:2048
	ds_read_b128 v[166:169], v166 offset:3072
	ds_read_b128 v[170:173], v182
	ds_read_b128 v[174:177], v182 offset:1024
	ds_read_b128 v[178:181], v182 offset:2048
	ds_read_b128 v[182:185], v182 offset:3072
	s_add_u32 s28, s28, 0x80000
	s_addc_u32 s29, s29, 0
	s_mov_b32 m0, s37
	v_lshl_add_u64 v[226:227], s[28:29], 0, v[130:131]
	ds_read_b128 v[186:189], v153 offset:32768
	ds_read_b128 v[190:193], v153 offset:33792
	ds_read_b128 v[194:197], v153 offset:34816
	ds_read_b128 v[198:201], v153 offset:35840
	ds_read_b128 v[202:205], v153 offset:36864
	ds_read_b128 v[206:209], v153 offset:37888
	ds_read_b128 v[210:213], v153 offset:38912
	ds_read_b128 v[214:217], v153 offset:39936
	global_load_lds_dwordx4 v[226:227], off
	v_lshl_add_u64 v[226:227], s[28:29], 0, v[134:135]
	s_mov_b32 m0, s38
	s_nop 0
	global_load_lds_dwordx4 v[226:227], off
	s_waitcnt vmcnt(8)
	s_waitcnt lgkmcnt(0)
	s_barrier
	s_waitcnt lgkmcnt(0)
	v_mfma_f32_16x16x32_bf16 v[124:127], v[154:157], v[186:189], v[124:127]
	v_mfma_f32_16x16x32_bf16 v[124:127], v[158:161], v[190:193], v[124:127]
	v_mfma_f32_16x16x32_bf16 v[120:123], v[162:165], v[186:189], v[120:123]
	v_mfma_f32_16x16x32_bf16 v[120:123], v[166:169], v[190:193], v[120:123]
	v_mfma_f32_16x16x32_bf16 v[104:107], v[162:165], v[194:197], v[104:107]
	v_mfma_f32_16x16x32_bf16 v[104:107], v[166:169], v[198:201], v[104:107]
	v_mfma_f32_16x16x32_bf16 v[108:111], v[154:157], v[194:197], v[108:111]
	v_mfma_f32_16x16x32_bf16 v[108:111], v[158:161], v[198:201], v[108:111]
	v_mfma_f32_16x16x32_bf16 v[92:95], v[154:157], v[202:205], v[92:95]
	v_mfma_f32_16x16x32_bf16 v[92:95], v[158:161], v[206:209], v[92:95]
	v_mfma_f32_16x16x32_bf16 v[88:91], v[162:165], v[202:205], v[88:91]
	v_mfma_f32_16x16x32_bf16 v[88:91], v[166:169], v[206:209], v[88:91]
	v_mfma_f32_16x16x32_bf16 v[72:75], v[162:165], v[210:213], v[72:75]
	v_mfma_f32_16x16x32_bf16 v[72:75], v[166:169], v[214:217], v[72:75]
	v_mfma_f32_16x16x32_bf16 v[76:79], v[154:157], v[210:213], v[76:79]
	v_mfma_f32_16x16x32_bf16 v[76:79], v[158:161], v[214:217], v[76:79]
	v_mfma_f32_16x16x32_bf16 v[116:119], v[170:173], v[186:189], v[116:119]
	v_mfma_f32_16x16x32_bf16 v[116:119], v[174:177], v[190:193], v[116:119]
	v_mfma_f32_16x16x32_bf16 v[112:115], v[178:181], v[186:189], v[112:115]
	v_mfma_f32_16x16x32_bf16 v[112:115], v[182:185], v[190:193], v[112:115]
	v_mfma_f32_16x16x32_bf16 v[96:99], v[178:181], v[194:197], v[96:99]
	v_mfma_f32_16x16x32_bf16 v[96:99], v[182:185], v[198:201], v[96:99]
	v_mfma_f32_16x16x32_bf16 v[100:103], v[170:173], v[194:197], v[100:103]
	v_mfma_f32_16x16x32_bf16 v[100:103], v[174:177], v[198:201], v[100:103]
	v_mfma_f32_16x16x32_bf16 v[84:87], v[170:173], v[202:205], v[84:87]
	v_mfma_f32_16x16x32_bf16 v[84:87], v[174:177], v[206:209], v[84:87]
	v_mfma_f32_16x16x32_bf16 v[80:83], v[178:181], v[202:205], v[80:83]
	v_mfma_f32_16x16x32_bf16 v[80:83], v[182:185], v[206:209], v[80:83]
	v_mfma_f32_16x16x32_bf16 v[64:67], v[178:181], v[210:213], v[64:67]
	v_mfma_f32_16x16x32_bf16 v[64:67], v[182:185], v[214:217], v[64:67]
	v_mfma_f32_16x16x32_bf16 v[68:71], v[170:173], v[210:213], v[68:71]
	v_mfma_f32_16x16x32_bf16 v[68:71], v[174:177], v[214:217], v[68:71]
	s_barrier
	s_add_i32 s28, s50, s35
	v_lshl_add_u64 v[218:219], v[218:219], 0, s[14:15]
	s_mov_b32 m0, s28
	ds_read_b128 v[186:189], v153 offset:49152
	ds_read_b128 v[190:193], v153 offset:50176
	ds_read_b128 v[194:197], v153 offset:51200
	ds_read_b128 v[198:201], v153 offset:52224
	ds_read_b128 v[202:205], v153 offset:53248
	ds_read_b128 v[206:209], v153 offset:54272
	ds_read_b128 v[210:213], v153 offset:55296
	ds_read_b128 v[214:217], v153 offset:56320
	global_load_lds_dwordx4 v[218:219], off
	s_add_i32 m0, s28, 0x2000
	s_add_u32 s26, s26, 0x80080
	v_lshl_add_u64 v[218:219], v[220:221], 0, s[14:15]
	s_addc_u32 s27, s27, 0
	s_add_i32 s28, s51, s35
	global_load_lds_dwordx4 v[218:219], off
	v_lshl_add_u64 v[218:219], s[26:27], 0, v[132:133]
	s_mov_b32 m0, s28
	s_nop 0
	global_load_lds_dwordx4 v[218:219], off
	v_lshl_add_u64 v[218:219], s[26:27], 0, v[136:137]
	s_add_i32 m0, s28, 0x2000
	s_nop 0
	global_load_lds_dwordx4 v[218:219], off
	v_lshl_add_u64 v[218:219], v[222:223], 0, s[14:15]
	s_mov_b32 m0, s39
	s_nop 0
	global_load_lds_dwordx4 v[218:219], off
	v_lshl_add_u64 v[218:219], v[224:225], 0, s[14:15]
	s_mov_b32 m0, s40
	s_nop 0
	global_load_lds_dwordx4 v[218:219], off
	s_waitcnt vmcnt(8)
	s_waitcnt lgkmcnt(0)
	s_barrier
	s_waitcnt lgkmcnt(0)
	v_mfma_f32_16x16x32_bf16 v[60:63], v[154:157], v[186:189], v[60:63]
	v_mfma_f32_16x16x32_bf16 v[60:63], v[158:161], v[190:193], v[60:63]
	v_mfma_f32_16x16x32_bf16 v[56:59], v[162:165], v[186:189], v[56:59]
	v_mfma_f32_16x16x32_bf16 v[56:59], v[166:169], v[190:193], v[56:59]
	v_mfma_f32_16x16x32_bf16 v[40:43], v[162:165], v[194:197], v[40:43]
	v_mfma_f32_16x16x32_bf16 v[40:43], v[166:169], v[198:201], v[40:43]
	v_mfma_f32_16x16x32_bf16 v[44:47], v[154:157], v[194:197], v[44:47]
	v_mfma_f32_16x16x32_bf16 v[44:47], v[158:161], v[198:201], v[44:47]
	v_mfma_f32_16x16x32_bf16 v[28:31], v[154:157], v[202:205], v[28:31]
	v_mfma_f32_16x16x32_bf16 v[28:31], v[158:161], v[206:209], v[28:31]
	v_mfma_f32_16x16x32_bf16 v[24:27], v[162:165], v[202:205], v[24:27]
	v_mfma_f32_16x16x32_bf16 v[24:27], v[166:169], v[206:209], v[24:27]
	v_mfma_f32_16x16x32_bf16 v[8:11], v[162:165], v[210:213], v[8:11]
	v_mfma_f32_16x16x32_bf16 v[8:11], v[166:169], v[214:217], v[8:11]
	v_mfma_f32_16x16x32_bf16 v[12:15], v[154:157], v[210:213], v[12:15]
	v_mfma_f32_16x16x32_bf16 v[12:15], v[158:161], v[214:217], v[12:15]
	v_mfma_f32_16x16x32_bf16 v[52:55], v[170:173], v[186:189], v[52:55]
	v_mfma_f32_16x16x32_bf16 v[52:55], v[174:177], v[190:193], v[52:55]
	v_mfma_f32_16x16x32_bf16 v[48:51], v[178:181], v[186:189], v[48:51]
	v_mfma_f32_16x16x32_bf16 v[48:51], v[182:185], v[190:193], v[48:51]
	v_mfma_f32_16x16x32_bf16 v[32:35], v[178:181], v[194:197], v[32:35]
	v_mfma_f32_16x16x32_bf16 v[32:35], v[182:185], v[198:201], v[32:35]
	v_mfma_f32_16x16x32_bf16 v[36:39], v[170:173], v[194:197], v[36:39]
	v_mfma_f32_16x16x32_bf16 v[36:39], v[174:177], v[198:201], v[36:39]
	v_mfma_f32_16x16x32_bf16 v[20:23], v[170:173], v[202:205], v[20:23]
	v_mfma_f32_16x16x32_bf16 v[20:23], v[174:177], v[206:209], v[20:23]
	v_mfma_f32_16x16x32_bf16 v[16:19], v[178:181], v[202:205], v[16:19]
	v_mfma_f32_16x16x32_bf16 v[16:19], v[182:185], v[206:209], v[16:19]
	v_mfma_f32_16x16x32_bf16 v[0:3], v[178:181], v[210:213], v[0:3]
	v_mfma_f32_16x16x32_bf16 v[0:3], v[182:185], v[214:217], v[0:3]
	v_mfma_f32_16x16x32_bf16 v[4:7], v[170:173], v[210:213], v[4:7]
	v_mfma_f32_16x16x32_bf16 v[4:7], v[174:177], v[214:217], v[4:7]
	s_barrier
	s_add_i32 s49, s49, 2
	s_add_u32 s24, s24, 0x100
	s_addc_u32 s25, s25, 0
	s_cmp_gt_u32 s49, 29
	s_cbranch_scc0 .LBB0_585
	s_add_u32 s24, s45, 0xffffff00
	s_addc_u32 s25, s46, -1
	s_andn2_b64 vcc, exec, s[4:5]
	s_cbranch_vccnz .LBB0_588
	v_mov_b32_e32 v0, 0
	s_mov_b32 s8, s16
	s_mov_b32 s10, s18
	s_mov_b64 s[12:13], s[22:23]
	s_mov_b32 s41, s44
	v_mov_b32_e32 v1, v0
	v_mov_b32_e32 v2, v0
	v_mov_b32_e32 v3, v0
	v_mov_b32_e32 v4, v0
	v_mov_b32_e32 v5, v0
	v_mov_b32_e32 v6, v0
	v_mov_b32_e32 v7, v0
	v_mov_b32_e32 v16, v0
	v_mov_b32_e32 v17, v0
	v_mov_b32_e32 v18, v0
	v_mov_b32_e32 v19, v0
	v_mov_b32_e32 v20, v0
	v_mov_b32_e32 v21, v0
	v_mov_b32_e32 v22, v0
	v_mov_b32_e32 v23, v0
	v_mov_b32_e32 v32, v0
	v_mov_b32_e32 v33, v0
	v_mov_b32_e32 v34, v0
	v_mov_b32_e32 v35, v0
	v_mov_b32_e32 v36, v0
	v_mov_b32_e32 v37, v0
	v_mov_b32_e32 v38, v0
	v_mov_b32_e32 v39, v0
	v_mov_b32_e32 v48, v0
	v_mov_b32_e32 v49, v0
	v_mov_b32_e32 v50, v0
	v_mov_b32_e32 v51, v0
	v_mov_b32_e32 v52, v0
	v_mov_b32_e32 v53, v0
	v_mov_b32_e32 v54, v0
	v_mov_b32_e32 v55, v0
	v_mov_b32_e32 v8, v0
	v_mov_b32_e32 v9, v0
	v_mov_b32_e32 v10, v0
	v_mov_b32_e32 v11, v0
	v_mov_b32_e32 v12, v0
	v_mov_b32_e32 v13, v0
	v_mov_b32_e32 v14, v0
	v_mov_b32_e32 v15, v0
	v_mov_b32_e32 v24, v0
	v_mov_b32_e32 v25, v0
	v_mov_b32_e32 v26, v0
	v_mov_b32_e32 v27, v0
	v_mov_b32_e32 v28, v0
	v_mov_b32_e32 v29, v0
	v_mov_b32_e32 v30, v0
	v_mov_b32_e32 v31, v0
	v_mov_b32_e32 v40, v0
	v_mov_b32_e32 v41, v0
	v_mov_b32_e32 v42, v0
	v_mov_b32_e32 v43, v0
	v_mov_b32_e32 v44, v0
	v_mov_b32_e32 v45, v0
	v_mov_b32_e32 v46, v0
	v_mov_b32_e32 v47, v0
	v_mov_b32_e32 v56, v0
	v_mov_b32_e32 v57, v0
	v_mov_b32_e32 v58, v0
	v_mov_b32_e32 v59, v0
	v_mov_b32_e32 v60, v0
	v_mov_b32_e32 v61, v0
	v_mov_b32_e32 v62, v0
	v_mov_b32_e32 v63, v0
	v_mov_b32_e32 v64, v0
	v_mov_b32_e32 v65, v0
	v_mov_b32_e32 v66, v0
	v_mov_b32_e32 v67, v0
	v_mov_b32_e32 v68, v0
	v_mov_b32_e32 v69, v0
	v_mov_b32_e32 v70, v0
	v_mov_b32_e32 v71, v0
	v_mov_b32_e32 v80, v0
	v_mov_b32_e32 v81, v0
	v_mov_b32_e32 v82, v0
	v_mov_b32_e32 v83, v0
	v_mov_b32_e32 v84, v0
	v_mov_b32_e32 v85, v0
	v_mov_b32_e32 v86, v0
	v_mov_b32_e32 v87, v0
	v_mov_b32_e32 v96, v0
	v_mov_b32_e32 v97, v0
	v_mov_b32_e32 v98, v0
	v_mov_b32_e32 v99, v0
	v_mov_b32_e32 v100, v0
	v_mov_b32_e32 v101, v0
	v_mov_b32_e32 v102, v0
	v_mov_b32_e32 v103, v0
	v_mov_b32_e32 v112, v0
	v_mov_b32_e32 v113, v0
	v_mov_b32_e32 v114, v0
	v_mov_b32_e32 v115, v0
	v_mov_b32_e32 v116, v0
	v_mov_b32_e32 v117, v0
	v_mov_b32_e32 v118, v0
	v_mov_b32_e32 v119, v0
	v_mov_b32_e32 v72, v0
	v_mov_b32_e32 v73, v0
	v_mov_b32_e32 v74, v0
	v_mov_b32_e32 v75, v0
	v_mov_b32_e32 v76, v0
	v_mov_b32_e32 v77, v0
	v_mov_b32_e32 v78, v0
	v_mov_b32_e32 v79, v0
	v_mov_b32_e32 v88, v0
	v_mov_b32_e32 v89, v0
	v_mov_b32_e32 v90, v0
	v_mov_b32_e32 v91, v0
	v_mov_b32_e32 v92, v0
	v_mov_b32_e32 v93, v0
	v_mov_b32_e32 v94, v0
	v_mov_b32_e32 v95, v0
	v_mov_b32_e32 v104, v0
	v_mov_b32_e32 v105, v0
	v_mov_b32_e32 v106, v0
	v_mov_b32_e32 v107, v0
	v_mov_b32_e32 v108, v0
	v_mov_b32_e32 v109, v0
	v_mov_b32_e32 v110, v0
	v_mov_b32_e32 v111, v0
	v_mov_b32_e32 v120, v0
	v_mov_b32_e32 v121, v0
	v_mov_b32_e32 v122, v0
	v_mov_b32_e32 v123, v0
	v_mov_b32_e32 v124, v0
	v_mov_b32_e32 v125, v0
	v_mov_b32_e32 v126, v0
	v_mov_b32_e32 v127, v0
	s_andn2_b64 vcc, exec, s[0:1]
	s_cbranch_vccnz .LBB0_589
	s_branch .LBB0_590

.LBB0_671:
	ds_read_b128 v[156:159], v151
	ds_read_b128 v[160:163], v151 offset:1024
	ds_read_b128 v[164:167], v151 offset:2048
	ds_read_b128 v[168:171], v151 offset:3072
	ds_read_b128 v[172:175], v152
	ds_read_b128 v[176:179], v152 offset:1024
	ds_read_b128 v[180:183], v152 offset:2048
	ds_read_b128 v[184:187], v152 offset:3072
	s_add_u32 s28, s26, 0xfff80080
	s_addc_u32 s29, s27, -1
	s_cmp_eq_u32 s53, 28
	s_cselect_b32 s31, s19, s29
	s_cselect_b32 s30, s49, s28
	s_cselect_b32 s29, s17, s52
	s_cselect_b32 s28, s50, s51
	v_lshl_add_u64 v[146:147], s[26:27], 0, v[138:139]
	s_add_i32 m0, s25, 0xc000
	ds_read_b128 v[188:191], v153
	ds_read_b128 v[192:195], v153 offset:1024
	ds_read_b128 v[196:199], v153 offset:2048
	ds_read_b128 v[200:203], v153 offset:3072
	ds_read_b128 v[204:207], v153 offset:4096
	ds_read_b128 v[208:211], v153 offset:5120
	ds_read_b128 v[212:215], v153 offset:6144
	ds_read_b128 v[216:219], v153 offset:7168
	global_load_lds_dwordx4 v[146:147], off
	v_lshl_add_u64 v[146:147], s[26:27], 0, v[140:141]
	s_add_i32 m0, s25, 0xe000
	s_nop 0
	global_load_lds_dwordx4 v[146:147], off
	s_waitcnt vmcnt(8)
	s_waitcnt lgkmcnt(0)
	s_barrier
	s_waitcnt lgkmcnt(0)
	v_mfma_f32_16x16x32_bf16 v[116:119], v[156:159], v[188:191], v[116:119]
	v_mfma_f32_16x16x32_bf16 v[116:119], v[160:163], v[192:195], v[116:119]
	v_mfma_f32_16x16x32_bf16 v[112:115], v[164:167], v[188:191], v[112:115]
	v_mfma_f32_16x16x32_bf16 v[112:115], v[168:171], v[192:195], v[112:115]
	v_mfma_f32_16x16x32_bf16 v[96:99], v[164:167], v[196:199], v[96:99]
	v_mfma_f32_16x16x32_bf16 v[96:99], v[168:171], v[200:203], v[96:99]
	v_mfma_f32_16x16x32_bf16 v[100:103], v[156:159], v[196:199], v[100:103]
	v_mfma_f32_16x16x32_bf16 v[100:103], v[160:163], v[200:203], v[100:103]
	v_mfma_f32_16x16x32_bf16 v[84:87], v[156:159], v[204:207], v[84:87]
	v_mfma_f32_16x16x32_bf16 v[84:87], v[160:163], v[208:211], v[84:87]
	v_mfma_f32_16x16x32_bf16 v[80:83], v[164:167], v[204:207], v[80:83]
	v_mfma_f32_16x16x32_bf16 v[80:83], v[168:171], v[208:211], v[80:83]
	v_mfma_f32_16x16x32_bf16 v[64:67], v[164:167], v[212:215], v[64:67]
	v_mfma_f32_16x16x32_bf16 v[64:67], v[168:171], v[216:219], v[64:67]
	v_mfma_f32_16x16x32_bf16 v[68:71], v[156:159], v[212:215], v[68:71]
	v_mfma_f32_16x16x32_bf16 v[68:71], v[160:163], v[216:219], v[68:71]
	v_mfma_f32_16x16x32_bf16 v[124:127], v[172:175], v[188:191], v[124:127]
	v_mfma_f32_16x16x32_bf16 v[124:127], v[176:179], v[192:195], v[124:127]
	v_mfma_f32_16x16x32_bf16 v[120:123], v[180:183], v[188:191], v[120:123]
	v_mfma_f32_16x16x32_bf16 v[120:123], v[184:187], v[192:195], v[120:123]
	v_mfma_f32_16x16x32_bf16 v[104:107], v[180:183], v[196:199], v[104:107]
	v_mfma_f32_16x16x32_bf16 v[104:107], v[184:187], v[200:203], v[104:107]
	v_mfma_f32_16x16x32_bf16 v[108:111], v[172:175], v[196:199], v[108:111]
	v_mfma_f32_16x16x32_bf16 v[108:111], v[176:179], v[200:203], v[108:111]
	v_mfma_f32_16x16x32_bf16 v[92:95], v[172:175], v[204:207], v[92:95]
	v_mfma_f32_16x16x32_bf16 v[92:95], v[176:179], v[208:211], v[92:95]
	v_mfma_f32_16x16x32_bf16 v[88:91], v[180:183], v[204:207], v[88:91]
	v_mfma_f32_16x16x32_bf16 v[88:91], v[184:187], v[208:211], v[88:91]
	v_mfma_f32_16x16x32_bf16 v[72:75], v[180:183], v[212:215], v[72:75]
	v_mfma_f32_16x16x32_bf16 v[72:75], v[184:187], v[216:219], v[72:75]
	v_mfma_f32_16x16x32_bf16 v[76:79], v[172:175], v[212:215], v[76:79]
	v_mfma_f32_16x16x32_bf16 v[76:79], v[176:179], v[216:219], v[76:79]
	s_barrier
	s_add_i32 s54, s46, s36
	v_lshl_add_u64 v[146:147], s[28:29], 0, v[134:135]
	s_mov_b32 m0, s54
	ds_read_b128 v[188:191], v153 offset:16384
	ds_read_b128 v[192:195], v153 offset:17408
	ds_read_b128 v[196:199], v153 offset:18432
	ds_read_b128 v[200:203], v153 offset:19456
	ds_read_b128 v[204:207], v153 offset:20480
	ds_read_b128 v[208:211], v153 offset:21504
	ds_read_b128 v[212:215], v153 offset:22528
	ds_read_b128 v[216:219], v153 offset:23552
	global_load_lds_dwordx4 v[146:147], off
	s_add_i32 m0, s54, 0x2000
	s_add_u32 s54, s28, 0x80000
	v_lshl_add_u64 v[220:221], s[28:29], 0, v[130:131]
	s_addc_u32 s55, s29, 0
	s_add_i32 s56, s47, s36
	global_load_lds_dwordx4 v[220:221], off
	v_lshl_add_u64 v[222:223], s[54:55], 0, v[134:135]
	s_mov_b32 m0, s56
	v_lshl_add_u64 v[224:225], s[30:31], 0, v[132:133]
	global_load_lds_dwordx4 v[222:223], off
	v_lshl_add_u64 v[222:223], s[54:55], 0, v[130:131]
	s_add_i32 m0, s56, 0x2000
	s_nop 0
	global_load_lds_dwordx4 v[222:223], off
	v_lshl_add_u64 v[222:223], s[30:31], 0, v[136:137]
	s_mov_b32 m0, s25
	s_nop 0
	global_load_lds_dwordx4 v[222:223], off
	s_mov_b32 m0, s39
	s_nop 0
	global_load_lds_dwordx4 v[224:225], off
	s_waitcnt vmcnt(8)
	s_waitcnt lgkmcnt(0)
	s_barrier
	s_waitcnt lgkmcnt(0)
	v_mfma_f32_16x16x32_bf16 v[52:55], v[156:159], v[188:191], v[52:55]
	v_mfma_f32_16x16x32_bf16 v[52:55], v[160:163], v[192:195], v[52:55]
	v_mfma_f32_16x16x32_bf16 v[48:51], v[164:167], v[188:191], v[48:51]
	v_mfma_f32_16x16x32_bf16 v[48:51], v[168:171], v[192:195], v[48:51]
	v_mfma_f32_16x16x32_bf16 v[32:35], v[164:167], v[196:199], v[32:35]
	v_mfma_f32_16x16x32_bf16 v[32:35], v[168:171], v[200:203], v[32:35]
	v_mfma_f32_16x16x32_bf16 v[36:39], v[156:159], v[196:199], v[36:39]
	v_mfma_f32_16x16x32_bf16 v[36:39], v[160:163], v[200:203], v[36:39]
	v_mfma_f32_16x16x32_bf16 v[20:23], v[156:159], v[204:207], v[20:23]
	v_mfma_f32_16x16x32_bf16 v[20:23], v[160:163], v[208:211], v[20:23]
	v_mfma_f32_16x16x32_bf16 v[16:19], v[164:167], v[204:207], v[16:19]
	v_mfma_f32_16x16x32_bf16 v[16:19], v[168:171], v[208:211], v[16:19]
	v_mfma_f32_16x16x32_bf16 v[0:3], v[164:167], v[212:215], v[0:3]
	v_mfma_f32_16x16x32_bf16 v[0:3], v[168:171], v[216:219], v[0:3]
	v_mfma_f32_16x16x32_bf16 v[8:11], v[156:159], v[212:215], v[8:11]
	v_mfma_f32_16x16x32_bf16 v[8:11], v[160:163], v[216:219], v[8:11]
	v_mfma_f32_16x16x32_bf16 v[60:63], v[172:175], v[188:191], v[60:63]
	v_mfma_f32_16x16x32_bf16 v[60:63], v[176:179], v[192:195], v[60:63]
	v_mfma_f32_16x16x32_bf16 v[56:59], v[180:183], v[188:191], v[56:59]
	v_mfma_f32_16x16x32_bf16 v[56:59], v[184:187], v[192:195], v[56:59]
	v_mfma_f32_16x16x32_bf16 v[40:43], v[180:183], v[196:199], v[40:43]
	v_mfma_f32_16x16x32_bf16 v[40:43], v[184:187], v[200:203], v[40:43]
	v_mfma_f32_16x16x32_bf16 v[44:47], v[172:175], v[196:199], v[44:47]
	v_mfma_f32_16x16x32_bf16 v[44:47], v[176:179], v[200:203], v[44:47]
	v_mfma_f32_16x16x32_bf16 v[28:31], v[172:175], v[204:207], v[28:31]
	v_mfma_f32_16x16x32_bf16 v[28:31], v[176:179], v[208:211], v[28:31]
	v_mfma_f32_16x16x32_bf16 v[24:27], v[180:183], v[204:207], v[24:27]
	v_mfma_f32_16x16x32_bf16 v[24:27], v[184:187], v[208:211], v[24:27]
	v_mfma_f32_16x16x32_bf16 v[4:7], v[180:183], v[212:215], v[4:7]
	v_mfma_f32_16x16x32_bf16 v[4:7], v[184:187], v[216:219], v[4:7]
	v_mfma_f32_16x16x32_bf16 v[12:15], v[172:175], v[212:215], v[12:15]
	v_mfma_f32_16x16x32_bf16 v[12:15], v[176:179], v[216:219], v[12:15]
	s_barrier
	s_add_i32 s54, 0, 0x18000
	v_add_u32_e32 v155, s54, v149
	s_add_i32 s55, 0, 0x1c000
	ds_read_b128 v[156:159], v155
	ds_read_b128 v[160:163], v155 offset:1024
	ds_read_b128 v[164:167], v155 offset:2048
	ds_read_b128 v[168:171], v155 offset:3072
	v_add_u32_e32 v155, s55, v149
	ds_read_b128 v[172:175], v155
	ds_read_b128 v[176:179], v155 offset:1024
	ds_read_b128 v[180:183], v155 offset:2048
	ds_read_b128 v[184:187], v155 offset:3072
	s_add_u32 s30, s30, 0x80000
	s_addc_u32 s31, s31, 0
	s_mov_b32 m0, s40
	v_lshl_add_u64 v[226:227], s[30:31], 0, v[136:137]
	ds_read_b128 v[188:191], v153 offset:32768
	ds_read_b128 v[192:195], v153 offset:33792
	ds_read_b128 v[196:199], v153 offset:34816
	ds_read_b128 v[200:203], v153 offset:35840
	ds_read_b128 v[204:207], v153 offset:36864
	ds_read_b128 v[208:211], v153 offset:37888
	ds_read_b128 v[212:215], v153 offset:38912
	ds_read_b128 v[216:219], v153 offset:39936
	global_load_lds_dwordx4 v[226:227], off
	v_lshl_add_u64 v[226:227], s[30:31], 0, v[132:133]
	s_mov_b32 m0, s41
	s_nop 0
	global_load_lds_dwordx4 v[226:227], off
	s_waitcnt vmcnt(8)
	s_waitcnt lgkmcnt(0)
	s_barrier
	s_waitcnt lgkmcnt(0)
	v_mfma_f32_16x16x32_bf16 v[116:119], v[156:159], v[188:191], v[116:119]
	v_mfma_f32_16x16x32_bf16 v[116:119], v[160:163], v[192:195], v[116:119]
	v_mfma_f32_16x16x32_bf16 v[112:115], v[164:167], v[188:191], v[112:115]
	v_mfma_f32_16x16x32_bf16 v[112:115], v[168:171], v[192:195], v[112:115]
	v_mfma_f32_16x16x32_bf16 v[96:99], v[164:167], v[196:199], v[96:99]
	v_mfma_f32_16x16x32_bf16 v[96:99], v[168:171], v[200:203], v[96:99]
	v_mfma_f32_16x16x32_bf16 v[100:103], v[156:159], v[196:199], v[100:103]
	v_mfma_f32_16x16x32_bf16 v[100:103], v[160:163], v[200:203], v[100:103]
	v_mfma_f32_16x16x32_bf16 v[84:87], v[156:159], v[204:207], v[84:87]
	v_mfma_f32_16x16x32_bf16 v[84:87], v[160:163], v[208:211], v[84:87]
	v_mfma_f32_16x16x32_bf16 v[80:83], v[164:167], v[204:207], v[80:83]
	v_mfma_f32_16x16x32_bf16 v[80:83], v[168:171], v[208:211], v[80:83]
	v_mfma_f32_16x16x32_bf16 v[64:67], v[164:167], v[212:215], v[64:67]
	v_mfma_f32_16x16x32_bf16 v[64:67], v[168:171], v[216:219], v[64:67]
	v_mfma_f32_16x16x32_bf16 v[68:71], v[156:159], v[212:215], v[68:71]
	v_mfma_f32_16x16x32_bf16 v[68:71], v[160:163], v[216:219], v[68:71]
	v_mfma_f32_16x16x32_bf16 v[124:127], v[172:175], v[188:191], v[124:127]
	v_mfma_f32_16x16x32_bf16 v[124:127], v[176:179], v[192:195], v[124:127]
	v_mfma_f32_16x16x32_bf16 v[120:123], v[180:183], v[188:191], v[120:123]
	v_mfma_f32_16x16x32_bf16 v[120:123], v[184:187], v[192:195], v[120:123]
	v_mfma_f32_16x16x32_bf16 v[104:107], v[180:183], v[196:199], v[104:107]
	v_mfma_f32_16x16x32_bf16 v[104:107], v[184:187], v[200:203], v[104:107]
	v_mfma_f32_16x16x32_bf16 v[108:111], v[172:175], v[196:199], v[108:111]
	v_mfma_f32_16x16x32_bf16 v[108:111], v[176:179], v[200:203], v[108:111]
	v_mfma_f32_16x16x32_bf16 v[92:95], v[172:175], v[204:207], v[92:95]
	v_mfma_f32_16x16x32_bf16 v[92:95], v[176:179], v[208:211], v[92:95]
	v_mfma_f32_16x16x32_bf16 v[88:91], v[180:183], v[204:207], v[88:91]
	v_mfma_f32_16x16x32_bf16 v[88:91], v[184:187], v[208:211], v[88:91]
	v_mfma_f32_16x16x32_bf16 v[72:75], v[180:183], v[212:215], v[72:75]
	v_mfma_f32_16x16x32_bf16 v[72:75], v[184:187], v[216:219], v[72:75]
	v_mfma_f32_16x16x32_bf16 v[76:79], v[172:175], v[212:215], v[76:79]
	v_mfma_f32_16x16x32_bf16 v[76:79], v[176:179], v[216:219], v[76:79]
	s_barrier
	s_add_i32 s30, s54, s36
	v_lshl_add_u64 v[146:147], v[146:147], 0, s[12:13]
	s_mov_b32 m0, s30
	ds_read_b128 v[188:191], v153 offset:49152
	ds_read_b128 v[192:195], v153 offset:50176
	ds_read_b128 v[196:199], v153 offset:51200
	ds_read_b128 v[200:203], v153 offset:52224
	ds_read_b128 v[204:207], v153 offset:53248
	ds_read_b128 v[208:211], v153 offset:54272
	ds_read_b128 v[212:215], v153 offset:55296
	ds_read_b128 v[216:219], v153 offset:56320
	global_load_lds_dwordx4 v[146:147], off
	s_add_i32 m0, s30, 0x2000
	s_add_u32 s28, s28, 0x80080
	v_lshl_add_u64 v[146:147], v[220:221], 0, s[12:13]
	s_addc_u32 s29, s29, 0
	s_add_i32 s30, s55, s36
	global_load_lds_dwordx4 v[146:147], off
	v_lshl_add_u64 v[146:147], s[28:29], 0, v[134:135]
	s_mov_b32 m0, s30
	s_nop 0
	global_load_lds_dwordx4 v[146:147], off
	v_lshl_add_u64 v[146:147], s[28:29], 0, v[130:131]
	s_add_i32 m0, s30, 0x2000
	s_nop 0
	global_load_lds_dwordx4 v[146:147], off
	v_lshl_add_u64 v[146:147], v[222:223], 0, s[12:13]
	s_mov_b32 m0, s43
	s_nop 0
	global_load_lds_dwordx4 v[146:147], off
	v_lshl_add_u64 v[146:147], v[224:225], 0, s[12:13]
	s_mov_b32 m0, s44
	s_nop 0
	global_load_lds_dwordx4 v[146:147], off
	s_waitcnt vmcnt(8)
	s_waitcnt lgkmcnt(0)
	s_barrier
	s_waitcnt lgkmcnt(0)
	v_mfma_f32_16x16x32_bf16 v[52:55], v[156:159], v[188:191], v[52:55]
	v_mfma_f32_16x16x32_bf16 v[52:55], v[160:163], v[192:195], v[52:55]
	v_mfma_f32_16x16x32_bf16 v[48:51], v[164:167], v[188:191], v[48:51]
	v_mfma_f32_16x16x32_bf16 v[48:51], v[168:171], v[192:195], v[48:51]
	v_mfma_f32_16x16x32_bf16 v[32:35], v[164:167], v[196:199], v[32:35]
	v_mfma_f32_16x16x32_bf16 v[32:35], v[168:171], v[200:203], v[32:35]
	v_mfma_f32_16x16x32_bf16 v[36:39], v[156:159], v[196:199], v[36:39]
	v_mfma_f32_16x16x32_bf16 v[36:39], v[160:163], v[200:203], v[36:39]
	v_mfma_f32_16x16x32_bf16 v[20:23], v[156:159], v[204:207], v[20:23]
	v_mfma_f32_16x16x32_bf16 v[20:23], v[160:163], v[208:211], v[20:23]
	v_mfma_f32_16x16x32_bf16 v[16:19], v[164:167], v[204:207], v[16:19]
	v_mfma_f32_16x16x32_bf16 v[16:19], v[168:171], v[208:211], v[16:19]
	v_mfma_f32_16x16x32_bf16 v[0:3], v[164:167], v[212:215], v[0:3]
	v_mfma_f32_16x16x32_bf16 v[0:3], v[168:171], v[216:219], v[0:3]
	v_mfma_f32_16x16x32_bf16 v[8:11], v[156:159], v[212:215], v[8:11]
	v_mfma_f32_16x16x32_bf16 v[8:11], v[160:163], v[216:219], v[8:11]
	v_mfma_f32_16x16x32_bf16 v[60:63], v[172:175], v[188:191], v[60:63]
	v_mfma_f32_16x16x32_bf16 v[60:63], v[176:179], v[192:195], v[60:63]
	v_mfma_f32_16x16x32_bf16 v[56:59], v[180:183], v[188:191], v[56:59]
	v_mfma_f32_16x16x32_bf16 v[56:59], v[184:187], v[192:195], v[56:59]
	v_mfma_f32_16x16x32_bf16 v[40:43], v[180:183], v[196:199], v[40:43]
	v_mfma_f32_16x16x32_bf16 v[40:43], v[184:187], v[200:203], v[40:43]
	v_mfma_f32_16x16x32_bf16 v[44:47], v[172:175], v[196:199], v[44:47]
	v_mfma_f32_16x16x32_bf16 v[44:47], v[176:179], v[200:203], v[44:47]
	v_mfma_f32_16x16x32_bf16 v[28:31], v[172:175], v[204:207], v[28:31]
	v_mfma_f32_16x16x32_bf16 v[28:31], v[176:179], v[208:211], v[28:31]
	v_mfma_f32_16x16x32_bf16 v[24:27], v[180:183], v[204:207], v[24:27]
	v_mfma_f32_16x16x32_bf16 v[24:27], v[184:187], v[208:211], v[24:27]
	v_mfma_f32_16x16x32_bf16 v[4:7], v[180:183], v[212:215], v[4:7]
	v_mfma_f32_16x16x32_bf16 v[4:7], v[184:187], v[216:219], v[4:7]
	v_mfma_f32_16x16x32_bf16 v[12:15], v[172:175], v[212:215], v[12:15]
	v_mfma_f32_16x16x32_bf16 v[12:15], v[176:179], v[216:219], v[12:15]
	s_barrier
	s_add_i32 s53, s53, 2
	s_add_u32 s26, s26, 0x100
	s_addc_u32 s27, s27, 0
	s_add_u32 s51, s51, 0x100
	s_addc_u32 s52, s52, 0
	s_cmp_gt_u32 s53, 29
	s_cbranch_scc0 .LBB0_671
	s_and_b64 vcc, exec, s[14:15]
	s_cbranch_vccz .LBB0_674
	s_barrier

.LBB0_849:
	v_add_u32_e32 v164, s40, v129
	v_add_u32_e32 v173, s41, v129
	s_add_u32 s22, s14, s20
	ds_read_b128 v[152:155], v164
	ds_read_b128 v[156:159], v164 offset:1024
	ds_read_b128 v[160:163], v164 offset:2048
	ds_read_b128 v[164:167], v164 offset:3072
	ds_read_b128 v[168:171], v173
	ds_read_b128 v[174:177], v173 offset:1024
	ds_read_b128 v[178:181], v173 offset:2048
	ds_read_b128 v[182:185], v173 offset:3072
	s_addc_u32 s23, s15, s21
	s_add_u32 s22, s22, 0x100
	s_addc_u32 s23, s23, 0
	s_add_u32 s48, s45, s20
	s_addc_u32 s49, s46, s21
	s_cmpk_eq_i32 s20, 0x2b00
	s_cselect_b32 s25, s19, s23
	s_cselect_b32 s24, s18, s22
	s_cselect_b32 s23, s7, s49
	s_cselect_b32 s22, s6, s48
	v_lshl_add_u64 v[218:219], v[146:147], 0, s[20:21]
	s_add_i32 m0, s33, 0xc000
	ds_read_b128 v[186:189], v151
	ds_read_b128 v[190:193], v151 offset:1024
	ds_read_b128 v[194:197], v151 offset:2048
	ds_read_b128 v[198:201], v151 offset:3072
	ds_read_b128 v[202:205], v151 offset:4096
	ds_read_b128 v[206:209], v151 offset:5120
	ds_read_b128 v[210:213], v151 offset:6144
	ds_read_b128 v[214:217], v151 offset:7168
	global_load_lds_dwordx4 v[218:219], off
	v_lshl_add_u64 v[218:219], v[148:149], 0, s[20:21]
	s_add_i32 m0, s33, 0xe000
	s_nop 0
	global_load_lds_dwordx4 v[218:219], off
	s_waitcnt vmcnt(8)
	s_waitcnt lgkmcnt(0)
	s_barrier
	s_waitcnt lgkmcnt(0)
	v_mfma_f32_16x16x32_bf16 v[124:127], v[152:155], v[186:189], v[124:127]
	v_mfma_f32_16x16x32_bf16 v[124:127], v[156:159], v[190:193], v[124:127]
	v_mfma_f32_16x16x32_bf16 v[120:123], v[160:163], v[186:189], v[120:123]
	v_mfma_f32_16x16x32_bf16 v[120:123], v[164:167], v[190:193], v[120:123]
	v_mfma_f32_16x16x32_bf16 v[104:107], v[160:163], v[194:197], v[104:107]
	v_mfma_f32_16x16x32_bf16 v[104:107], v[164:167], v[198:201], v[104:107]
	v_mfma_f32_16x16x32_bf16 v[108:111], v[152:155], v[194:197], v[108:111]
	v_mfma_f32_16x16x32_bf16 v[108:111], v[156:159], v[198:201], v[108:111]
	v_mfma_f32_16x16x32_bf16 v[92:95], v[152:155], v[202:205], v[92:95]
	v_mfma_f32_16x16x32_bf16 v[92:95], v[156:159], v[206:209], v[92:95]
	v_mfma_f32_16x16x32_bf16 v[88:91], v[160:163], v[202:205], v[88:91]
	v_mfma_f32_16x16x32_bf16 v[88:91], v[164:167], v[206:209], v[88:91]
	v_mfma_f32_16x16x32_bf16 v[72:75], v[160:163], v[210:213], v[72:75]
	v_mfma_f32_16x16x32_bf16 v[72:75], v[164:167], v[214:217], v[72:75]
	v_mfma_f32_16x16x32_bf16 v[76:79], v[152:155], v[210:213], v[76:79]
	v_mfma_f32_16x16x32_bf16 v[76:79], v[156:159], v[214:217], v[76:79]
	v_mfma_f32_16x16x32_bf16 v[116:119], v[168:171], v[186:189], v[116:119]
	v_mfma_f32_16x16x32_bf16 v[116:119], v[174:177], v[190:193], v[116:119]
	v_mfma_f32_16x16x32_bf16 v[112:115], v[178:181], v[186:189], v[112:115]
	v_mfma_f32_16x16x32_bf16 v[112:115], v[182:185], v[190:193], v[112:115]
	v_mfma_f32_16x16x32_bf16 v[96:99], v[178:181], v[194:197], v[96:99]
	v_mfma_f32_16x16x32_bf16 v[96:99], v[182:185], v[198:201], v[96:99]
	v_mfma_f32_16x16x32_bf16 v[100:103], v[168:171], v[194:197], v[100:103]
	v_mfma_f32_16x16x32_bf16 v[100:103], v[174:177], v[198:201], v[100:103]
	v_mfma_f32_16x16x32_bf16 v[84:87], v[168:171], v[202:205], v[84:87]
	v_mfma_f32_16x16x32_bf16 v[84:87], v[174:177], v[206:209], v[84:87]
	v_mfma_f32_16x16x32_bf16 v[80:83], v[178:181], v[202:205], v[80:83]
	v_mfma_f32_16x16x32_bf16 v[80:83], v[182:185], v[206:209], v[80:83]
	v_mfma_f32_16x16x32_bf16 v[64:67], v[178:181], v[210:213], v[64:67]
	v_mfma_f32_16x16x32_bf16 v[64:67], v[182:185], v[214:217], v[64:67]
	v_mfma_f32_16x16x32_bf16 v[68:71], v[168:171], v[210:213], v[68:71]
	v_mfma_f32_16x16x32_bf16 v[68:71], v[174:177], v[214:217], v[68:71]
	s_barrier
	s_add_i32 s48, s40, s31
	v_lshl_add_u64 v[218:219], s[22:23], 0, v[132:133]
	s_mov_b32 m0, s48
	ds_read_b128 v[186:189], v151 offset:16384
	ds_read_b128 v[190:193], v151 offset:17408
	ds_read_b128 v[194:197], v151 offset:18432
	ds_read_b128 v[198:201], v151 offset:19456
	ds_read_b128 v[202:205], v151 offset:20480
	ds_read_b128 v[206:209], v151 offset:21504
	ds_read_b128 v[210:213], v151 offset:22528
	ds_read_b128 v[214:217], v151 offset:23552
	global_load_lds_dwordx4 v[218:219], off
	s_add_i32 m0, s48, 0x2000
	s_add_u32 s48, s22, 0x160000
	v_lshl_add_u64 v[220:221], s[22:23], 0, v[136:137]
	s_addc_u32 s49, s23, 0
	s_add_i32 s50, s41, s31
	global_load_lds_dwordx4 v[220:221], off
	v_lshl_add_u64 v[222:223], s[48:49], 0, v[132:133]
	s_mov_b32 m0, s50
	v_lshl_add_u64 v[224:225], s[24:25], 0, v[134:135]
	global_load_lds_dwordx4 v[222:223], off
	v_lshl_add_u64 v[222:223], s[48:49], 0, v[136:137]
	s_add_i32 m0, s50, 0x2000
	s_nop 0
	global_load_lds_dwordx4 v[222:223], off
	v_lshl_add_u64 v[222:223], s[24:25], 0, v[130:131]
	s_mov_b32 m0, s33
	s_nop 0
	global_load_lds_dwordx4 v[222:223], off
	s_mov_b32 m0, s34
	s_nop 0
	global_load_lds_dwordx4 v[224:225], off
	s_waitcnt vmcnt(8)
	s_waitcnt lgkmcnt(0)
	s_barrier
	s_waitcnt lgkmcnt(0)
	v_mfma_f32_16x16x32_bf16 v[60:63], v[152:155], v[186:189], v[60:63]
	v_mfma_f32_16x16x32_bf16 v[60:63], v[156:159], v[190:193], v[60:63]
	v_mfma_f32_16x16x32_bf16 v[56:59], v[160:163], v[186:189], v[56:59]
	v_mfma_f32_16x16x32_bf16 v[56:59], v[164:167], v[190:193], v[56:59]
	v_mfma_f32_16x16x32_bf16 v[40:43], v[160:163], v[194:197], v[40:43]
	v_mfma_f32_16x16x32_bf16 v[40:43], v[164:167], v[198:201], v[40:43]
	v_mfma_f32_16x16x32_bf16 v[44:47], v[152:155], v[194:197], v[44:47]
	v_mfma_f32_16x16x32_bf16 v[44:47], v[156:159], v[198:201], v[44:47]
	v_mfma_f32_16x16x32_bf16 v[28:31], v[152:155], v[202:205], v[28:31]
	v_mfma_f32_16x16x32_bf16 v[28:31], v[156:159], v[206:209], v[28:31]
	v_mfma_f32_16x16x32_bf16 v[24:27], v[160:163], v[202:205], v[24:27]
	v_mfma_f32_16x16x32_bf16 v[24:27], v[164:167], v[206:209], v[24:27]
	v_mfma_f32_16x16x32_bf16 v[8:11], v[160:163], v[210:213], v[8:11]
	v_mfma_f32_16x16x32_bf16 v[8:11], v[164:167], v[214:217], v[8:11]
	v_mfma_f32_16x16x32_bf16 v[12:15], v[152:155], v[210:213], v[12:15]
	v_mfma_f32_16x16x32_bf16 v[12:15], v[156:159], v[214:217], v[12:15]
	v_mfma_f32_16x16x32_bf16 v[52:55], v[168:171], v[186:189], v[52:55]
	v_mfma_f32_16x16x32_bf16 v[52:55], v[174:177], v[190:193], v[52:55]
	v_mfma_f32_16x16x32_bf16 v[48:51], v[178:181], v[186:189], v[48:51]
	v_mfma_f32_16x16x32_bf16 v[48:51], v[182:185], v[190:193], v[48:51]
	v_mfma_f32_16x16x32_bf16 v[32:35], v[178:181], v[194:197], v[32:35]
	v_mfma_f32_16x16x32_bf16 v[32:35], v[182:185], v[198:201], v[32:35]
	v_mfma_f32_16x16x32_bf16 v[36:39], v[168:171], v[194:197], v[36:39]
	v_mfma_f32_16x16x32_bf16 v[36:39], v[174:177], v[198:201], v[36:39]
	v_mfma_f32_16x16x32_bf16 v[20:23], v[168:171], v[202:205], v[20:23]
	v_mfma_f32_16x16x32_bf16 v[20:23], v[174:177], v[206:209], v[20:23]
	v_mfma_f32_16x16x32_bf16 v[16:19], v[178:181], v[202:205], v[16:19]
	v_mfma_f32_16x16x32_bf16 v[16:19], v[182:185], v[206:209], v[16:19]
	v_mfma_f32_16x16x32_bf16 v[0:3], v[178:181], v[210:213], v[0:3]
	v_mfma_f32_16x16x32_bf16 v[0:3], v[182:185], v[214:217], v[0:3]
	v_mfma_f32_16x16x32_bf16 v[4:7], v[168:171], v[210:213], v[4:7]
	v_mfma_f32_16x16x32_bf16 v[4:7], v[174:177], v[214:217], v[4:7]
	s_barrier
	s_add_i32 s48, 0, 0x18000
	s_add_i32 s49, 0, 0x1c000
	v_add_u32_e32 v164, s48, v129
	v_add_u32_e32 v173, s49, v129
	ds_read_b128 v[152:155], v164
	ds_read_b128 v[156:159], v164 offset:1024
	ds_read_b128 v[160:163], v164 offset:2048
	ds_read_b128 v[164:167], v164 offset:3072
	ds_read_b128 v[168:171], v173
	ds_read_b128 v[174:177], v173 offset:1024
	ds_read_b128 v[178:181], v173 offset:2048
	ds_read_b128 v[182:185], v173 offset:3072
	s_add_u32 s24, s24, 0x160000
	s_addc_u32 s25, s25, 0
	s_mov_b32 m0, s35
	v_lshl_add_u64 v[226:227], s[24:25], 0, v[130:131]
	ds_read_b128 v[186:189], v151 offset:32768
	ds_read_b128 v[190:193], v151 offset:33792
	ds_read_b128 v[194:197], v151 offset:34816
	ds_read_b128 v[198:201], v151 offset:35840
	ds_read_b128 v[202:205], v151 offset:36864
	ds_read_b128 v[206:209], v151 offset:37888
	ds_read_b128 v[210:213], v151 offset:38912
	ds_read_b128 v[214:217], v151 offset:39936
	global_load_lds_dwordx4 v[226:227], off
	v_lshl_add_u64 v[226:227], s[24:25], 0, v[134:135]
	s_mov_b32 m0, s36
	s_nop 0
	global_load_lds_dwordx4 v[226:227], off
	s_waitcnt vmcnt(8)
	s_waitcnt lgkmcnt(0)
	s_barrier
	s_waitcnt lgkmcnt(0)
	v_mfma_f32_16x16x32_bf16 v[124:127], v[152:155], v[186:189], v[124:127]
	v_mfma_f32_16x16x32_bf16 v[124:127], v[156:159], v[190:193], v[124:127]
	v_mfma_f32_16x16x32_bf16 v[120:123], v[160:163], v[186:189], v[120:123]
	v_mfma_f32_16x16x32_bf16 v[120:123], v[164:167], v[190:193], v[120:123]
	v_mfma_f32_16x16x32_bf16 v[104:107], v[160:163], v[194:197], v[104:107]
	v_mfma_f32_16x16x32_bf16 v[104:107], v[164:167], v[198:201], v[104:107]
	v_mfma_f32_16x16x32_bf16 v[108:111], v[152:155], v[194:197], v[108:111]
	v_mfma_f32_16x16x32_bf16 v[108:111], v[156:159], v[198:201], v[108:111]
	v_mfma_f32_16x16x32_bf16 v[92:95], v[152:155], v[202:205], v[92:95]
	v_mfma_f32_16x16x32_bf16 v[92:95], v[156:159], v[206:209], v[92:95]
	v_mfma_f32_16x16x32_bf16 v[88:91], v[160:163], v[202:205], v[88:91]
	v_mfma_f32_16x16x32_bf16 v[88:91], v[164:167], v[206:209], v[88:91]
	v_mfma_f32_16x16x32_bf16 v[72:75], v[160:163], v[210:213], v[72:75]
	v_mfma_f32_16x16x32_bf16 v[72:75], v[164:167], v[214:217], v[72:75]
	v_mfma_f32_16x16x32_bf16 v[76:79], v[152:155], v[210:213], v[76:79]
	v_mfma_f32_16x16x32_bf16 v[76:79], v[156:159], v[214:217], v[76:79]
	v_mfma_f32_16x16x32_bf16 v[116:119], v[168:171], v[186:189], v[116:119]
	v_mfma_f32_16x16x32_bf16 v[116:119], v[174:177], v[190:193], v[116:119]
	v_mfma_f32_16x16x32_bf16 v[112:115], v[178:181], v[186:189], v[112:115]
	v_mfma_f32_16x16x32_bf16 v[112:115], v[182:185], v[190:193], v[112:115]
	v_mfma_f32_16x16x32_bf16 v[96:99], v[178:181], v[194:197], v[96:99]
	v_mfma_f32_16x16x32_bf16 v[96:99], v[182:185], v[198:201], v[96:99]
	v_mfma_f32_16x16x32_bf16 v[100:103], v[168:171], v[194:197], v[100:103]
	v_mfma_f32_16x16x32_bf16 v[100:103], v[174:177], v[198:201], v[100:103]
	v_mfma_f32_16x16x32_bf16 v[84:87], v[168:171], v[202:205], v[84:87]
	v_mfma_f32_16x16x32_bf16 v[84:87], v[174:177], v[206:209], v[84:87]
	v_mfma_f32_16x16x32_bf16 v[80:83], v[178:181], v[202:205], v[80:83]
	v_mfma_f32_16x16x32_bf16 v[80:83], v[182:185], v[206:209], v[80:83]
	v_mfma_f32_16x16x32_bf16 v[64:67], v[178:181], v[210:213], v[64:67]
	v_mfma_f32_16x16x32_bf16 v[64:67], v[182:185], v[214:217], v[64:67]
	v_mfma_f32_16x16x32_bf16 v[68:71], v[168:171], v[210:213], v[68:71]
	v_mfma_f32_16x16x32_bf16 v[68:71], v[174:177], v[214:217], v[68:71]
	s_barrier
	s_add_i32 s24, s48, s31
	v_lshl_add_u64 v[218:219], v[218:219], 0, s[16:17]
	s_mov_b32 m0, s24
	ds_read_b128 v[186:189], v151 offset:49152
	ds_read_b128 v[190:193], v151 offset:50176
	ds_read_b128 v[194:197], v151 offset:51200
	ds_read_b128 v[198:201], v151 offset:52224
	ds_read_b128 v[202:205], v151 offset:53248
	ds_read_b128 v[206:209], v151 offset:54272
	ds_read_b128 v[210:213], v151 offset:55296
	ds_read_b128 v[214:217], v151 offset:56320
	global_load_lds_dwordx4 v[218:219], off
	s_add_i32 m0, s24, 0x2000
	s_add_u32 s22, s22, 0x160080
	v_lshl_add_u64 v[218:219], v[220:221], 0, s[16:17]
	s_addc_u32 s23, s23, 0
	s_add_i32 s24, s49, s31
	global_load_lds_dwordx4 v[218:219], off
	v_lshl_add_u64 v[218:219], s[22:23], 0, v[132:133]
	s_mov_b32 m0, s24
	s_nop 0
	global_load_lds_dwordx4 v[218:219], off
	v_lshl_add_u64 v[218:219], s[22:23], 0, v[136:137]
	s_add_i32 m0, s24, 0x2000
	s_nop 0
	global_load_lds_dwordx4 v[218:219], off
	v_lshl_add_u64 v[218:219], v[222:223], 0, s[16:17]
	s_mov_b32 m0, s37
	s_nop 0
	global_load_lds_dwordx4 v[218:219], off
	v_lshl_add_u64 v[218:219], v[224:225], 0, s[16:17]
	s_mov_b32 m0, s38
	s_nop 0
	global_load_lds_dwordx4 v[218:219], off
	s_waitcnt vmcnt(8)
	s_waitcnt lgkmcnt(0)
	s_barrier
	s_waitcnt lgkmcnt(0)
	v_mfma_f32_16x16x32_bf16 v[60:63], v[152:155], v[186:189], v[60:63]
	v_mfma_f32_16x16x32_bf16 v[60:63], v[156:159], v[190:193], v[60:63]
	v_mfma_f32_16x16x32_bf16 v[56:59], v[160:163], v[186:189], v[56:59]
	v_mfma_f32_16x16x32_bf16 v[56:59], v[164:167], v[190:193], v[56:59]
	v_mfma_f32_16x16x32_bf16 v[40:43], v[160:163], v[194:197], v[40:43]
	v_mfma_f32_16x16x32_bf16 v[40:43], v[164:167], v[198:201], v[40:43]
	v_mfma_f32_16x16x32_bf16 v[44:47], v[152:155], v[194:197], v[44:47]
	v_mfma_f32_16x16x32_bf16 v[44:47], v[156:159], v[198:201], v[44:47]
	v_mfma_f32_16x16x32_bf16 v[28:31], v[152:155], v[202:205], v[28:31]
	v_mfma_f32_16x16x32_bf16 v[28:31], v[156:159], v[206:209], v[28:31]
	v_mfma_f32_16x16x32_bf16 v[24:27], v[160:163], v[202:205], v[24:27]
	v_mfma_f32_16x16x32_bf16 v[24:27], v[164:167], v[206:209], v[24:27]
	v_mfma_f32_16x16x32_bf16 v[8:11], v[160:163], v[210:213], v[8:11]
	v_mfma_f32_16x16x32_bf16 v[8:11], v[164:167], v[214:217], v[8:11]
	v_mfma_f32_16x16x32_bf16 v[12:15], v[152:155], v[210:213], v[12:15]
	v_mfma_f32_16x16x32_bf16 v[12:15], v[156:159], v[214:217], v[12:15]
	v_mfma_f32_16x16x32_bf16 v[52:55], v[168:171], v[186:189], v[52:55]
	v_mfma_f32_16x16x32_bf16 v[52:55], v[174:177], v[190:193], v[52:55]
	v_mfma_f32_16x16x32_bf16 v[48:51], v[178:181], v[186:189], v[48:51]
	v_mfma_f32_16x16x32_bf16 v[48:51], v[182:185], v[190:193], v[48:51]
	v_mfma_f32_16x16x32_bf16 v[32:35], v[178:181], v[194:197], v[32:35]
	v_mfma_f32_16x16x32_bf16 v[32:35], v[182:185], v[198:201], v[32:35]
	v_mfma_f32_16x16x32_bf16 v[36:39], v[168:171], v[194:197], v[36:39]
	v_mfma_f32_16x16x32_bf16 v[36:39], v[174:177], v[198:201], v[36:39]
	v_mfma_f32_16x16x32_bf16 v[20:23], v[168:171], v[202:205], v[20:23]
	v_mfma_f32_16x16x32_bf16 v[20:23], v[174:177], v[206:209], v[20:23]
	v_mfma_f32_16x16x32_bf16 v[16:19], v[178:181], v[202:205], v[16:19]
	v_mfma_f32_16x16x32_bf16 v[16:19], v[182:185], v[206:209], v[16:19]
	v_mfma_f32_16x16x32_bf16 v[0:3], v[178:181], v[210:213], v[0:3]
	v_mfma_f32_16x16x32_bf16 v[0:3], v[182:185], v[214:217], v[0:3]
	v_mfma_f32_16x16x32_bf16 v[4:7], v[168:171], v[210:213], v[4:7]
	v_mfma_f32_16x16x32_bf16 v[4:7], v[174:177], v[214:217], v[4:7]
	s_barrier
	s_add_i32 s47, s47, 2
	s_add_u32 s20, s20, 0x100
	s_addc_u32 s21, s21, 0
	s_cmpk_gt_u32 s47, 0x55
	s_cbranch_scc0 .LBB0_849
	s_add_u32 s20, s45, 0xffffff00
	s_addc_u32 s21, s46, -1
	s_and_b64 vcc, exec, s[4:5]
	s_cbranch_vccnz .LBB0_852
	v_mov_b32_e32 v0, 0
	s_mov_b32 s12, s42
	s_mov_b32 s13, s43
	s_mov_b64 s[14:15], s[18:19]
	s_mov_b32 s39, s44
	v_mov_b32_e32 v1, v0
	v_mov_b32_e32 v2, v0
	v_mov_b32_e32 v3, v0
	v_mov_b32_e32 v4, v0
	v_mov_b32_e32 v5, v0
	v_mov_b32_e32 v6, v0
	v_mov_b32_e32 v7, v0
	v_mov_b32_e32 v16, v0
	v_mov_b32_e32 v17, v0
	v_mov_b32_e32 v18, v0
	v_mov_b32_e32 v19, v0
	v_mov_b32_e32 v20, v0
	v_mov_b32_e32 v21, v0
	v_mov_b32_e32 v22, v0
	v_mov_b32_e32 v23, v0
	v_mov_b32_e32 v32, v0
	v_mov_b32_e32 v33, v0
	v_mov_b32_e32 v34, v0
	v_mov_b32_e32 v35, v0
	v_mov_b32_e32 v36, v0
	v_mov_b32_e32 v37, v0
	v_mov_b32_e32 v38, v0
	v_mov_b32_e32 v39, v0
	v_mov_b32_e32 v48, v0
	v_mov_b32_e32 v49, v0
	v_mov_b32_e32 v50, v0
	v_mov_b32_e32 v51, v0
	v_mov_b32_e32 v52, v0
	v_mov_b32_e32 v53, v0
	v_mov_b32_e32 v54, v0
	v_mov_b32_e32 v55, v0
	v_mov_b32_e32 v8, v0
	v_mov_b32_e32 v9, v0
	v_mov_b32_e32 v10, v0
	v_mov_b32_e32 v11, v0
	v_mov_b32_e32 v12, v0
	v_mov_b32_e32 v13, v0
	v_mov_b32_e32 v14, v0
	v_mov_b32_e32 v15, v0
	v_mov_b32_e32 v24, v0
	v_mov_b32_e32 v25, v0
	v_mov_b32_e32 v26, v0
	v_mov_b32_e32 v27, v0
	v_mov_b32_e32 v28, v0
	v_mov_b32_e32 v29, v0
	v_mov_b32_e32 v30, v0
	v_mov_b32_e32 v31, v0
	v_mov_b32_e32 v40, v0
	v_mov_b32_e32 v41, v0
	v_mov_b32_e32 v42, v0
	v_mov_b32_e32 v43, v0
	v_mov_b32_e32 v44, v0
	v_mov_b32_e32 v45, v0
	v_mov_b32_e32 v46, v0
	v_mov_b32_e32 v47, v0
	v_mov_b32_e32 v56, v0
	v_mov_b32_e32 v57, v0
	v_mov_b32_e32 v58, v0
	v_mov_b32_e32 v59, v0
	v_mov_b32_e32 v60, v0
	v_mov_b32_e32 v61, v0
	v_mov_b32_e32 v62, v0
	v_mov_b32_e32 v63, v0
	v_mov_b32_e32 v64, v0
	v_mov_b32_e32 v65, v0
	v_mov_b32_e32 v66, v0
	v_mov_b32_e32 v67, v0
	v_mov_b32_e32 v68, v0
	v_mov_b32_e32 v69, v0
	v_mov_b32_e32 v70, v0
	v_mov_b32_e32 v71, v0
	v_mov_b32_e32 v80, v0
	v_mov_b32_e32 v81, v0
	v_mov_b32_e32 v82, v0
	v_mov_b32_e32 v83, v0
	v_mov_b32_e32 v84, v0
	v_mov_b32_e32 v85, v0
	v_mov_b32_e32 v86, v0
	v_mov_b32_e32 v87, v0
	v_mov_b32_e32 v96, v0
	v_mov_b32_e32 v97, v0
	v_mov_b32_e32 v98, v0
	v_mov_b32_e32 v99, v0
	v_mov_b32_e32 v100, v0
	v_mov_b32_e32 v101, v0
	v_mov_b32_e32 v102, v0
	v_mov_b32_e32 v103, v0
	v_mov_b32_e32 v112, v0
	v_mov_b32_e32 v113, v0
	v_mov_b32_e32 v114, v0
	v_mov_b32_e32 v115, v0
	v_mov_b32_e32 v116, v0
	v_mov_b32_e32 v117, v0
	v_mov_b32_e32 v118, v0
	v_mov_b32_e32 v119, v0
	v_mov_b32_e32 v72, v0
	v_mov_b32_e32 v73, v0
	v_mov_b32_e32 v74, v0
	v_mov_b32_e32 v75, v0
	v_mov_b32_e32 v76, v0
	v_mov_b32_e32 v77, v0
	v_mov_b32_e32 v78, v0
	v_mov_b32_e32 v79, v0
	v_mov_b32_e32 v88, v0
	v_mov_b32_e32 v89, v0
	v_mov_b32_e32 v90, v0
	v_mov_b32_e32 v91, v0
	v_mov_b32_e32 v92, v0
	v_mov_b32_e32 v93, v0
	v_mov_b32_e32 v94, v0
	v_mov_b32_e32 v95, v0
	v_mov_b32_e32 v104, v0
	v_mov_b32_e32 v105, v0
	v_mov_b32_e32 v106, v0
	v_mov_b32_e32 v107, v0
	v_mov_b32_e32 v108, v0
	v_mov_b32_e32 v109, v0
	v_mov_b32_e32 v110, v0
	v_mov_b32_e32 v111, v0
	v_mov_b32_e32 v120, v0
	v_mov_b32_e32 v121, v0
	v_mov_b32_e32 v122, v0
	v_mov_b32_e32 v123, v0
	v_mov_b32_e32 v124, v0
	v_mov_b32_e32 v125, v0
	v_mov_b32_e32 v126, v0
	v_mov_b32_e32 v127, v0
	s_andn2_b64 vcc, exec, s[0:1]
	s_cbranch_vccnz .LBB0_853
	s_branch .LBB0_854
